# acquire at arrival: each workgroup's buffer_inv sc1 is issued and waited for when it arrives at a grid barrier (before its arrival atomic) instead of after the release; no cached loads happen between
# speedup vs baseline: 1.0364x; 1.0338x over previous
.LBB0_44:
	s_waitcnt vmcnt(0)
	v_mov_b32_e32 v182, 0
	v_mov_b32_e32 v180, 0
	s_waitcnt lgkmcnt(0)
	s_barrier
	s_and_saveexec_b64 s[0:1], s[94:95]
	s_cbranch_execz .LBB0_95
	s_add_u32 s4, s20, 0x1d750200
	s_addc_u32 s5, s21, 0
	s_add_u32 s6, s20, 0x1d750400
	s_addc_u32 s7, s21, 0
	s_add_u32 s8, s20, 0x1d750500
	s_addc_u32 s9, s21, 0
	s_add_u32 s10, s20, 0x1d750600
	s_addc_u32 s11, s21, 0
	s_add_u32 s12, s20, 0x1d750700
	s_addc_u32 s13, s21, 0
	s_add_u32 s14, s20, 0x1d750800
	s_addc_u32 s15, s21, 0
	s_add_u32 s16, s20, 0x1d750900
	s_addc_u32 s17, s21, 0
	s_add_u32 s28, s20, 0x1d750a00
	s_addc_u32 s29, s21, 0
	s_add_u32 s30, s20, 0x1d750b00
	s_addc_u32 s31, s21, 0
	s_add_u32 s34, s20, 0x1d750c00
	s_addc_u32 s35, s21, 0
	s_add_u32 s46, s20, 0x1d750d00
	s_addc_u32 s47, s21, 0
	s_add_u32 s62, s20, 0x1d750e00
	s_addc_u32 s63, s21, 0
	s_add_u32 s64, s20, 0x1d750f00
	s_addc_u32 s65, s21, 0
	s_add_u32 s68, s20, 0x1d751000
	s_addc_u32 s69, s21, 0
	s_add_u32 s70, s20, 0x1d751100
	s_addc_u32 s71, s21, 0
	s_add_u32 s72, s20, 0x1d751200
	s_addc_u32 s73, s21, 0
	s_mul_i32 s33, s23, s19
	s_add_u32 s74, s20, 0x1d751300
	s_mul_i32 s33, s33, s22
	s_addc_u32 s75, s21, 0
	s_mov_b32 s82, 1
	v_mov_b32_e32 v16, 0
	s_waitcnt vmcnt(0) expcnt(0) lgkmcnt(0)
	buffer_inv sc1
	s_waitcnt vmcnt(0)
	s_branch .LBB0_47

.LBB0_73:
	s_or_b64 exec, exec, s[10:11]
	s_waitcnt vmcnt(0)
	s_waitcnt vmcnt(0)

.LBB0_91:
	s_or_b64 exec, exec, s[4:5]
	s_mov_b64 s[4:5], exec
	v_mbcnt_lo_u32_b32 v0, s4, 0
	v_mbcnt_hi_u32_b32 v0, s5, v0
	v_cmp_eq_u32_e32 vcc, 0, v0
	s_waitcnt vmcnt(0)
	s_and_saveexec_b64 s[10:11], vcc
	s_cbranch_execz .LBB0_93
	s_bcnt1_i32_b64 s4, s[4:5]
	v_mov_b32_e32 v0, 0x2000
	v_mov_b32_e32 v1, s4
	global_atomic_add v0, v1, s[6:7] offset:1024

.LBB0_411:
	s_waitcnt vmcnt(0)
	s_waitcnt vmcnt(0)
	s_barrier
	s_and_saveexec_b64 s[0:1], s[94:95]
	s_cbranch_execz .LBB0_464
	v_cmp_eq_u32_e32 vcc, 0, v180
	s_waitcnt vmcnt(0) expcnt(0) lgkmcnt(0)
	buffer_inv sc1
	s_waitcnt vmcnt(0)
	s_and_saveexec_b64 s[4:5], vcc
	s_cbranch_execz .LBB0_427
	s_add_u32 s6, s20, 0x1d750200
	s_addc_u32 s7, s21, 0
	s_add_u32 s8, s20, 0x1d750400
	s_addc_u32 s9, s21, 0
	s_add_u32 s10, s20, 0x1d750500
	s_addc_u32 s11, s21, 0
	s_add_u32 s12, s20, 0x1d750600
	s_addc_u32 s13, s21, 0
	s_add_u32 s14, s20, 0x1d750700
	s_addc_u32 s15, s21, 0
	s_add_u32 s16, s20, 0x1d750800
	s_addc_u32 s17, s21, 0
	s_add_u32 s34, s20, 0x1d750900
	s_addc_u32 s35, s21, 0
	s_add_u32 s46, s20, 0x1d750a00
	s_addc_u32 s47, s21, 0
	s_add_u32 s62, s20, 0x1d750b00
	s_addc_u32 s63, s21, 0
	s_add_u32 s64, s20, 0x1d750c00
	s_addc_u32 s65, s21, 0
	s_add_u32 s68, s20, 0x1d750d00
	s_addc_u32 s69, s21, 0
	s_add_u32 s70, s20, 0x1d750e00
	s_addc_u32 s71, s21, 0
	s_add_u32 s72, s20, 0x1d750f00
	s_addc_u32 s73, s21, 0
	s_add_u32 s74, s20, 0x1d751000
	s_addc_u32 s75, s21, 0
	s_add_u32 s76, s20, 0x1d751100
	s_addc_u32 s77, s21, 0
	s_add_u32 s78, s20, 0x1d751200
	s_addc_u32 s79, s21, 0
	s_mul_i32 s29, s23, s19
	s_add_u32 s80, s20, 0x1d751300
	s_mul_i32 s29, s29, s22
	s_addc_u32 s81, s21, 0
	s_mov_b32 s33, 1
	v_mov_b32_e32 v16, 0
	s_branch .LBB0_415

.LBB0_442:
	s_or_b64 exec, exec, s[8:9]
	s_waitcnt vmcnt(0)
	s_waitcnt vmcnt(0)

.LBB0_460:
	s_or_b64 exec, exec, s[8:9]
	s_mov_b64 s[8:9], exec
	v_mbcnt_lo_u32_b32 v0, s8, 0
	v_mbcnt_hi_u32_b32 v0, s9, v0
	v_cmp_eq_u32_e32 vcc, 0, v0
	s_waitcnt vmcnt(0)
	s_and_saveexec_b64 s[10:11], vcc
	s_cbranch_execz .LBB0_462
	s_bcnt1_i32_b64 s8, s[8:9]
	v_mov_b32_e32 v0, 0x2000
	v_mov_b32_e32 v1, s8
	global_atomic_add v0, v1, s[4:5] offset:1024

.LBB0_735:
	s_waitcnt vmcnt(0)
	s_barrier
	s_and_saveexec_b64 s[0:1], s[94:95]
	s_cbranch_execz .LBB0_788
	v_cmp_eq_u32_e32 vcc, 0, v180
	s_waitcnt vmcnt(0) expcnt(0) lgkmcnt(0)
	buffer_inv sc1
	s_waitcnt vmcnt(0)
	s_and_saveexec_b64 s[4:5], vcc
	s_cbranch_execz .LBB0_751
	s_add_u32 s6, s20, 0x1d750200
	s_addc_u32 s7, s21, 0
	s_add_u32 s8, s20, 0x1d750400
	s_addc_u32 s9, s21, 0
	s_add_u32 s10, s20, 0x1d750500
	s_addc_u32 s11, s21, 0
	s_add_u32 s12, s20, 0x1d750600
	s_addc_u32 s13, s21, 0
	s_add_u32 s14, s20, 0x1d750700
	s_addc_u32 s15, s21, 0
	s_add_u32 s16, s20, 0x1d750800
	s_addc_u32 s17, s21, 0
	s_add_u32 s34, s20, 0x1d750900
	s_addc_u32 s35, s21, 0
	s_add_u32 s36, s20, 0x1d750a00
	s_addc_u32 s37, s21, 0
	s_add_u32 s38, s20, 0x1d750b00
	s_addc_u32 s39, s21, 0
	s_add_u32 s46, s20, 0x1d750c00
	s_addc_u32 s47, s21, 0
	s_add_u32 s56, s20, 0x1d750d00
	s_addc_u32 s57, s21, 0
	s_add_u32 s62, s20, 0x1d750e00
	s_addc_u32 s63, s21, 0
	s_add_u32 s64, s20, 0x1d750f00
	s_addc_u32 s65, s21, 0
	s_add_u32 s66, s20, 0x1d751000
	s_addc_u32 s67, s21, 0
	s_add_u32 s68, s20, 0x1d751100
	s_addc_u32 s69, s21, 0
	s_add_u32 s70, s20, 0x1d751200
	s_addc_u32 s71, s21, 0
	s_mul_i32 s29, s23, s19
	s_add_u32 s72, s20, 0x1d751300
	s_mul_i32 s29, s29, s22
	s_addc_u32 s73, s21, 0
	s_mov_b32 s33, 1
	v_mov_b32_e32 v16, 0
	s_branch .LBB0_739

.LBB0_931:
	s_waitcnt vmcnt(0)
	s_barrier
	s_and_saveexec_b64 s[0:1], s[94:95]
	s_cbranch_execz .LBB0_984
	v_cmp_eq_u32_e32 vcc, 0, v180
	s_waitcnt vmcnt(0) expcnt(0) lgkmcnt(0)
	buffer_inv sc1
	s_waitcnt vmcnt(0)
	s_and_saveexec_b64 s[4:5], vcc
	s_cbranch_execz .LBB0_947
	s_add_u32 s6, s20, 0x1d750200
	s_addc_u32 s7, s21, 0
	s_add_u32 s8, s20, 0x1d750400
	s_addc_u32 s9, s21, 0
	s_add_u32 s10, s20, 0x1d750500
	s_addc_u32 s11, s21, 0
	s_add_u32 s12, s20, 0x1d750600
	s_addc_u32 s13, s21, 0
	s_add_u32 s14, s20, 0x1d750700
	s_addc_u32 s15, s21, 0
	s_add_u32 s16, s20, 0x1d750800
	s_addc_u32 s17, s21, 0
	s_add_u32 s34, s20, 0x1d750900
	s_addc_u32 s35, s21, 0
	s_add_u32 s36, s20, 0x1d750a00
	s_addc_u32 s37, s21, 0
	s_add_u32 s38, s20, 0x1d750b00
	s_addc_u32 s39, s21, 0
	s_add_u32 s42, s20, 0x1d750c00
	s_addc_u32 s43, s21, 0
	s_add_u32 s46, s20, 0x1d750d00
	s_addc_u32 s47, s21, 0
	s_add_u32 s56, s20, 0x1d750e00
	s_addc_u32 s57, s21, 0
	s_add_u32 s62, s20, 0x1d750f00
	s_addc_u32 s63, s21, 0
	s_add_u32 s64, s20, 0x1d751000
	s_addc_u32 s65, s21, 0
	s_add_u32 s66, s20, 0x1d751100
	s_addc_u32 s67, s21, 0
	s_add_u32 s68, s20, 0x1d751200
	s_addc_u32 s69, s21, 0
	s_mul_i32 s29, s23, s19
	s_add_u32 s70, s20, 0x1d751300
	s_mul_i32 s29, s29, s22
	s_addc_u32 s71, s21, 0
	s_mov_b32 s33, 1
	v_mov_b32_e32 v16, 0
	s_branch .LBB0_935

.LBB0_1032:
	s_waitcnt vmcnt(0)
	s_barrier
	s_and_saveexec_b64 s[0:1], s[94:95]
	s_cbranch_execz .LBB0_1085
	v_cmp_eq_u32_e32 vcc, 0, v180
	s_waitcnt vmcnt(0) expcnt(0) lgkmcnt(0)
	buffer_inv sc1
	s_waitcnt vmcnt(0)
	s_and_saveexec_b64 s[4:5], vcc
	s_cbranch_execz .LBB0_1048
	s_add_u32 s6, s20, 0x1d750200
	s_addc_u32 s7, s21, 0
	s_add_u32 s8, s20, 0x1d750400
	s_addc_u32 s9, s21, 0
	s_add_u32 s10, s20, 0x1d750500
	s_addc_u32 s11, s21, 0
	s_add_u32 s12, s20, 0x1d750600
	s_addc_u32 s13, s21, 0
	s_add_u32 s14, s20, 0x1d750700
	s_addc_u32 s15, s21, 0
	s_add_u32 s16, s20, 0x1d750800
	s_addc_u32 s17, s21, 0
	s_add_u32 s34, s20, 0x1d750900
	s_addc_u32 s35, s21, 0
	s_add_u32 s36, s20, 0x1d750a00
	s_addc_u32 s37, s21, 0
	s_add_u32 s38, s20, 0x1d750b00
	s_addc_u32 s39, s21, 0
	s_add_u32 s42, s20, 0x1d750c00
	s_addc_u32 s43, s21, 0
	s_add_u32 s46, s20, 0x1d750d00
	s_addc_u32 s47, s21, 0
	s_add_u32 s56, s20, 0x1d750e00
	s_addc_u32 s57, s21, 0
	s_add_u32 s58, s20, 0x1d750f00
	s_addc_u32 s59, s21, 0
	s_add_u32 s60, s20, 0x1d751000
	s_addc_u32 s61, s21, 0
	s_add_u32 s62, s20, 0x1d751100
	s_addc_u32 s63, s21, 0
	s_add_u32 s64, s20, 0x1d751200
	s_addc_u32 s65, s21, 0
	s_mul_i32 s29, s23, s19
	s_add_u32 s66, s20, 0x1d751300
	s_mul_i32 s29, s29, s22
	s_addc_u32 s67, s21, 0
	s_mov_b32 s33, 1
	v_mov_b32_e32 v16, 0
	s_branch .LBB0_1036

.LBB0_1096:
	s_waitcnt vmcnt(0)
	s_barrier
	s_and_saveexec_b64 s[0:1], s[94:95]
	s_cbranch_execz .LBB0_1149
	v_cmp_eq_u32_e32 vcc, 0, v180
	s_waitcnt vmcnt(0) expcnt(0) lgkmcnt(0)
	buffer_inv sc1
	s_waitcnt vmcnt(0)
	s_and_saveexec_b64 s[4:5], vcc
	s_cbranch_execz .LBB0_1112
	s_add_u32 s6, s20, 0x1d750200
	s_addc_u32 s7, s21, 0
	s_add_u32 s8, s20, 0x1d750400
	s_addc_u32 s9, s21, 0
	s_add_u32 s10, s20, 0x1d750500
	s_addc_u32 s11, s21, 0
	s_add_u32 s12, s20, 0x1d750600
	s_addc_u32 s13, s21, 0
	s_add_u32 s14, s20, 0x1d750700
	s_addc_u32 s15, s21, 0
	s_add_u32 s16, s20, 0x1d750800
	s_addc_u32 s17, s21, 0
	s_add_u32 s34, s20, 0x1d750900
	s_addc_u32 s35, s21, 0
	s_add_u32 s36, s20, 0x1d750a00
	s_addc_u32 s37, s21, 0
	s_add_u32 s38, s20, 0x1d750b00
	s_addc_u32 s39, s21, 0
	s_add_u32 s40, s20, 0x1d750c00
	s_addc_u32 s41, s21, 0
	s_add_u32 s42, s20, 0x1d750d00
	s_addc_u32 s43, s21, 0
	s_add_u32 s44, s20, 0x1d750e00
	s_addc_u32 s45, s21, 0
	s_add_u32 s46, s20, 0x1d750f00
	s_addc_u32 s47, s21, 0
	s_add_u32 s56, s20, 0x1d751000
	s_addc_u32 s57, s21, 0
	s_add_u32 s58, s20, 0x1d751100
	s_addc_u32 s59, s21, 0
	s_add_u32 s60, s20, 0x1d751200
	s_addc_u32 s61, s21, 0
	s_mul_i32 s29, s23, s19
	s_add_u32 s62, s20, 0x1d751300
	s_mul_i32 s29, s29, s22
	s_addc_u32 s63, s21, 0
	s_mov_b32 s33, 1
	v_mov_b32_e32 v16, 0
	s_branch .LBB0_1100

.LBB0_1168:
	s_waitcnt vmcnt(0)
	s_waitcnt vmcnt(0)
	s_barrier
	s_and_saveexec_b64 s[0:1], s[94:95]
	s_cbranch_execz .LBB0_1220
	v_cmp_eq_u32_e32 vcc, 0, v180
	s_waitcnt vmcnt(0) expcnt(0) lgkmcnt(0)
	buffer_inv sc1
	s_waitcnt vmcnt(0)
	s_and_saveexec_b64 s[4:5], vcc
	s_cbranch_execz .LBB0_1184
	s_add_u32 s8, s20, 0x1d750200
	s_addc_u32 s9, s21, 0
	s_add_u32 s10, s20, 0x1d750400
	s_addc_u32 s11, s21, 0
	s_add_u32 s12, s20, 0x1d750500
	s_addc_u32 s13, s21, 0
	s_add_u32 s14, s20, 0x1d750600
	s_addc_u32 s15, s21, 0
	s_add_u32 s16, s20, 0x1d750700
	s_addc_u32 s17, s21, 0
	s_add_u32 s18, s20, 0x1d750800
	s_mul_i32 s23, s23, s19
	s_addc_u32 s19, s21, 0
	s_add_u32 s28, s20, 0x1d750900
	s_addc_u32 s29, s21, 0
	s_add_u32 s30, s20, 0x1d750a00
	s_addc_u32 s31, s21, 0
	s_add_u32 s34, s20, 0x1d750b00
	s_addc_u32 s35, s21, 0
	s_add_u32 s36, s20, 0x1d750c00
	s_addc_u32 s37, s21, 0
	s_add_u32 s38, s20, 0x1d750d00
	s_addc_u32 s39, s21, 0
	s_add_u32 s40, s20, 0x1d750e00
	s_addc_u32 s41, s21, 0
	s_add_u32 s42, s20, 0x1d750f00
	s_addc_u32 s43, s21, 0
	s_add_u32 s44, s20, 0x1d751000
	s_addc_u32 s45, s21, 0
	s_add_u32 s46, s20, 0x1d751100
	s_addc_u32 s47, s21, 0
	s_add_u32 s56, s20, 0x1d751200
	s_addc_u32 s57, s21, 0
	s_add_u32 s58, s20, 0x1d751300
	s_mul_i32 s23, s23, s22
	s_addc_u32 s59, s21, 0
	s_mov_b32 s33, 1
	v_mov_b32_e32 v16, 0
	s_branch .LBB0_1172

.LBB0_1217:
	s_or_b64 exec, exec, s[8:9]
	s_mov_b64 s[8:9], exec
	v_mbcnt_lo_u32_b32 v0, s8, 0
	v_mbcnt_hi_u32_b32 v0, s9, v0
	v_cmp_eq_u32_e32 vcc, 0, v0
	s_waitcnt vmcnt(0)
	s_and_saveexec_b64 s[10:11], vcc
	s_cbranch_execz .LBB0_1219
	s_bcnt1_i32_b64 s3, s[8:9]
	v_mov_b32_e32 v0, 0x2000
	v_mov_b32_e32 v1, s3
	global_atomic_add v0, v1, s[4:5] offset:1024
